# v15 + 7 phases whose outputs are all 16-byte stores (P1 P3 P4 P7 P9 P11 P14) store write-through (sc1); their grid barriers skip the L2 writeback
# baseline (speedup 1.0000x reference)
.LBB0_245:
	s_andn2_saveexec_b64 s[6:7], s[6:7]
	s_cbranch_execz .LBB0_265
	s_mov_b64 s[8:9], exec
	s_nop 0
	s_waitcnt lgkmcnt(0)
	s_waitcnt vmcnt(0)
	v_mbcnt_lo_u32_b32 v1, s8, 0
	v_mbcnt_hi_u32_b32 v1, s9, v1
	v_cmp_eq_u32_e32 vcc, 0, v1
	s_and_saveexec_b64 s[12:13], vcc
	s_cbranch_execz .LBB0_248
	s_bcnt1_i32_b64 s3, s[8:9]
	v_mov_b32_e32 v2, 0x7000
	v_mov_b32_e32 v3, s3
	global_atomic_add v2, v2, v3, s[84:85] offset:1024 sc0

.LBB0_425:
	s_andn2_saveexec_b64 s[6:7], s[6:7]
	s_cbranch_execz .LBB0_445
	s_mov_b64 s[8:9], exec
	s_nop 0
	s_waitcnt lgkmcnt(0)
	s_waitcnt vmcnt(0)
	v_mbcnt_lo_u32_b32 v1, s8, 0
	v_mbcnt_hi_u32_b32 v1, s9, v1
	v_cmp_eq_u32_e32 vcc, 0, v1
	s_and_saveexec_b64 s[10:11], vcc
	s_cbranch_execz .LBB0_428
	s_bcnt1_i32_b64 s3, s[8:9]
	v_mov_b32_e32 v2, 0x7000
	v_mov_b32_e32 v3, s3
	global_atomic_add v2, v2, v3, s[84:85] offset:1024 sc0

.LBB0_1388:
	s_andn2_saveexec_b64 s[4:5], s[4:5]
	s_cbranch_execz .LBB0_1408
	s_mov_b64 s[6:7], exec
	s_nop 0
	s_waitcnt lgkmcnt(0)
	s_waitcnt vmcnt(0)
	v_mbcnt_lo_u32_b32 v1, s6, 0
	v_mbcnt_hi_u32_b32 v1, s7, v1
	v_cmp_eq_u32_e32 vcc, 0, v1
	s_and_saveexec_b64 s[8:9], vcc
	s_cbranch_execz .LBB0_1391
	s_bcnt1_i32_b64 s6, s[6:7]
	v_mov_b32_e32 v2, 0x7000
	v_mov_b32_e32 v3, s6
	global_atomic_add v2, v2, v3, s[84:85] offset:1024 sc0
